# attention: two loop bodies - fast body with softmax reference 0 (no per-element subtract) while scores stay within +-64, per-wave fallback to the running-max deferred-rescale body
# speedup vs baseline: 1.0423x; 1.0223x over previous
; DI void dattn_unit2(const bf16_t* __restrict__ Qg, const bf16_t* __restrict__ Kg, const bf16_t* __restrict__ Vg, bf16_t* __restrict__ Og,
;                     int ntiles, int wave_tiles, float lam, const float* __restrict__ gsub, lds_t* shm) {
;     ...
;   f32x16 O[2][NC];
; #pragma unroll
;   for (int m = 0; m < 2; ++m)
; #pragma unroll
;     for (int c = 0; c < NC; ++c)
; #pragma unroll
;       for (int i = 0; i < 16; ++i) O[m][c][i] = 0.f;
;   float mrun[2] = {-INFINITY, -INFINITY}, lrun[2] = {0.f, 0.f};
;   const unsigned q4 = (lane & 15) >> 2, pp = lane & 3, blk = (lane >> 4) & 1;
;   const unsigned xk = (l31 >> 2) & 3, kbase = 2048u * (l31 >> 3) + 64u * (l31 & 7);
;   const unsigned ka0 = kbase + 16u * ((unsigned)h ^ xk), ka2 = kbase + 16u * ((2u + h) ^ xk);
;   const unsigned vrow = 64u * (4u * h + q4), cl = 2u * blk + (pp >> 1);
;   const unsigned va0 = VRING + vrow + 16u * (cl ^ (unsigned)h) + 8u * (pp & 1), va1 = VRING + vrow + 16u * (cl ^ ((unsigned)h ^ 2u)) + 8u * (pp & 1);
;   WAIT_V(6); BAR;
;   if (grp == 1) { WAIT_V(4); BAR; }
;   int slot = 0;
;   for (int kt = 0; kt < ntiles; ++kt) {
;     const int slot2 = slot >= 1 ? slot - 1 : 2;
;     issueK(kt + 2, slot2);
;     const float msk = (kt < wave_tiles) ? 0.f : -INFINITY;
;     const unsigned so = slot * 16384;
;     lds_t* K0 = shm + (so + ka0); lds_t* K2 = shm + (so + ka2);
;     bf16x8 P[2][2][2]; float alpha[2]; bool resc[2];
; #pragma unroll
;     for (int m = 0; m < 2; ++m) {
;       f32x16 s[2];
; #pragma unroll
;       for (int kb = 0; kb < 2; ++kb)
; #pragma unroll
;         for (int i = 0; i < 16; ++i) s[kb][i] = 0.f;
; #pragma unroll
;       for (int ss = 0; ss < 4; ++ss) {
;         const bf16x8 qv = *LDSP(const bf16x8, Qst + ((ss & 1) ? ka2 : ka0) + 512 * (ss >> 1) + 1024 * m);
; #pragma unroll
;         for (int kb = 0; kb < 2; ++kb) {
;           const bf16x8 kf = *LDSP(const bf16x8, ((ss & 1) ? K2 : K0) + kb * 8192 + 512 * (ss >> 1) + 1024 * m);
;           s[kb] = MFMA32(kf, qv, s[kb]);
;         }
;       }
;       float mx = s[0][0];
; #pragma unroll
;       for (int i = 1; i < 16; ++i) mx = fmaxf(mx, s[0][i]);
; #pragma unroll
;       for (int i = 0; i < 16; ++i) mx = fmaxf(mx, s[1][i]);
;       { const auto sw = __builtin_amdgcn_permlane32_swap(__float_as_uint(mx), __float_as_uint(mx), false, false); mx = fmaxf(__uint_as_float(sw[0]), __uint_as_float(sw[1])) + msk; }
.LBB0_417:
	v_lshlrev_b32_e32 v7, 6, v0
	v_lshrrev_b32_e32 v4, 5, v0
	v_and_b32_e32 v3, 3, v3
	v_lshlrev_b32_e32 v6, 8, v0
	v_and_b32_e32 v7, 0x1c0, v7
	v_bfe_u32 v5, v0, 5, 1
	v_and_or_b32 v6, v6, s22, v7
	v_bitop3_b32 v4, v4, v3, 1 bitop3:0x6c
	v_lshl_or_b32 v218, v4, 4, v6
	v_or_b32_e32 v4, 2, v5
	v_bitop3_b32 v3, v5, v3, 2 bitop3:0x36
	v_and_b32_e32 v221, 0xc0, v1
	v_and_b32_e32 v1, 2, v2
	v_bfe_u32 v2, v0, 1, 1
	v_lshlrev_b32_e32 v0, 3, v0
	v_lshl_or_b32 v219, v3, 4, v6
	v_bitop3_b32 v3, v1, v5, v2 bitop3:0x36
	v_and_b32_e32 v223, 8, v0
	v_bitop3_b32 v0, v1, v4, v2 bitop3:0x36
	v_mov_b32_e32 v96, v193
	v_mov_b32_e32 v97, v193
	v_mov_b32_e32 v110, v193
	v_mov_b32_e32 v111, v193
	s_lshl_b32 s58, s54, 2
	v_lshlrev_b32_e32 v220, 8, v5
	v_lshlrev_b32_e32 v222, 4, v3
	v_lshlrev_b32_e32 v224, 4, v0
	v_mov_b32_e32 v98, v193
	v_mov_b32_e32 v99, v193
	v_mov_b32_e32 v100, v193
	v_mov_b32_e32 v101, v193
	v_mov_b32_e32 v102, v193
	v_mov_b32_e32 v103, v193
	v_mov_b32_e32 v104, v193
	v_mov_b32_e32 v105, v193
	v_mov_b32_e32 v106, v193
	v_mov_b32_e32 v107, v193
	v_mov_b32_e32 v108, v193
	v_mov_b32_e32 v109, v193
	v_mov_b32_e32 v198, 0xff800000
	v_mov_b32_e32 v200, 0
	v_mov_b64_e32 v[64:65], v[96:97]
	v_mov_b64_e32 v[32:33], v[96:97]
	v_mov_b64_e32 v[0:1], v[96:97]
	v_mov_b64_e32 v[126:127], v[110:111]
	v_mov_b64_e32 v[80:81], v[96:97]
	v_mov_b64_e32 v[48:49], v[96:97]
	v_mov_b64_e32 v[16:17], v[96:97]
	s_xor_b64 s[40:41], s[4:5], -1
	s_lshl_b64 s[42:43], s[6:7], 10
	v_mov_b32_e32 v197, v193
	s_add_i32 s54, s58, s19
	s_or_b32 s55, s58, 3
	s_add_i32 s58, s58, 4
	s_mov_b32 s59, 0
	v_add_u32_e32 v225, s52, v218
	v_mov_b64_e32 v[66:67], v[98:99]
	v_mov_b64_e32 v[68:69], v[100:101]
	v_mov_b64_e32 v[70:71], v[102:103]
	v_mov_b64_e32 v[72:73], v[104:105]
	v_mov_b64_e32 v[74:75], v[106:107]
	v_mov_b64_e32 v[76:77], v[108:109]
	v_mov_b64_e32 v[78:79], v[110:111]
	v_mov_b64_e32 v[34:35], v[98:99]
	v_mov_b64_e32 v[36:37], v[100:101]
	v_mov_b64_e32 v[38:39], v[102:103]
	v_mov_b64_e32 v[40:41], v[104:105]
	v_mov_b64_e32 v[42:43], v[106:107]
	v_mov_b64_e32 v[44:45], v[108:109]
	v_mov_b64_e32 v[46:47], v[110:111]
	v_mov_b64_e32 v[2:3], v[98:99]
	v_mov_b64_e32 v[4:5], v[100:101]
	v_mov_b64_e32 v[6:7], v[102:103]
	v_mov_b64_e32 v[8:9], v[104:105]
	v_mov_b64_e32 v[10:11], v[106:107]
	v_mov_b64_e32 v[12:13], v[108:109]
	v_mov_b64_e32 v[14:15], v[110:111]
	v_mov_b64_e32 v[124:125], v[108:109]
	v_mov_b64_e32 v[122:123], v[106:107]
	v_mov_b64_e32 v[120:121], v[104:105]
	v_mov_b64_e32 v[118:119], v[102:103]
	v_mov_b64_e32 v[116:117], v[100:101]
	v_mov_b64_e32 v[114:115], v[98:99]
	v_mov_b64_e32 v[112:113], v[96:97]
	v_mov_b64_e32 v[82:83], v[98:99]
	v_mov_b64_e32 v[84:85], v[100:101]
	v_mov_b64_e32 v[86:87], v[102:103]
	v_mov_b64_e32 v[88:89], v[104:105]
	v_mov_b64_e32 v[90:91], v[106:107]
	v_mov_b64_e32 v[92:93], v[108:109]
	v_mov_b64_e32 v[94:95], v[110:111]
	v_mov_b64_e32 v[50:51], v[98:99]
	v_mov_b64_e32 v[52:53], v[100:101]
	v_mov_b64_e32 v[54:55], v[102:103]
	v_mov_b64_e32 v[56:57], v[104:105]
	v_mov_b64_e32 v[58:59], v[106:107]
	v_mov_b64_e32 v[60:61], v[108:109]
	v_mov_b64_e32 v[62:63], v[110:111]
	v_mov_b64_e32 v[18:19], v[98:99]
	v_mov_b64_e32 v[20:21], v[100:101]
	v_mov_b64_e32 v[22:23], v[102:103]
	v_mov_b64_e32 v[24:25], v[104:105]
	v_mov_b64_e32 v[26:27], v[106:107]
	v_mov_b64_e32 v[28:29], v[108:109]
	v_mov_b64_e32 v[30:31], v[110:111]
	s_mov_b32 s60, 0
	v_mov_b32_e32 v201, v200
	v_mov_b32_e32 v199, v198
	s_mov_b32 s98, 0
	v_mov_b32_e32 v217, 0x42800000
	v_add3_u32 v255, v220, v221, v222
	v_add3_u32 v195, v220, v221, v224
	v_add_u32_e32 v255, v255, v223
	v_add_u32_e32 v195, v195, v223
.LBB0_419:
	s_cmp_lg_u32 s98, 0
	s_cbranch_scc1 .Ldas_top
.Ldaf_top:
	s_add_i32 s4, s60, 2
	s_lshl_b32 s6, s59, 14
	s_min_i32 s4, s4, s55
	s_add_i32 s5, s6, 0xffffc000
	s_cmp_gt_i32 s59, 0
	s_cselect_b32 s5, s5, 0x8000
	s_add_i32 s62, s53, s5
	s_lshl_b32 s63, s4, 17
	s_add_u32 s4, s8, s63
	s_addc_u32 s5, s9, 0
	s_mov_b32 m0, s62
	s_add_i32 s61, s6, 0
	global_load_lds_dwordx4 v192, s[4:5]
	s_add_i32 m0, s62, 0x2000
	s_cmp_gt_i32 s60, s54
	global_load_lds_dwordx4 v196, s[4:5]
	s_cbranch_scc1 .Ldaf_maskA
	v_add_u32_e32 v202, s61, v218
	v_add_u32_e32 v242, s52, v219
	ds_read_b128 v[128:131], v202
	ds_read_b128 v[132:135], v225
	ds_read_b128 v[144:147], v225 offset:512
	ds_read_b128 v[148:151], v202 offset:512
	v_add_u32_e32 v207, s61, v219
	s_waitcnt lgkmcnt(0)
	v_mfma_f32_32x32x16_bf16 v[160:175], v[128:131], v[132:135], 0
	ds_read_b128 v[128:131], v202 offset:8192
	ds_read_b128 v[152:155], v202 offset:8704
	ds_read_b128 v[156:159], v207
	ds_read_b128 v[176:179], v242
	ds_read_b128 v[180:183], v242 offset:512
	ds_read_b128 v[184:187], v207 offset:512
	s_waitcnt lgkmcnt(0)
	v_mfma_f32_32x32x16_bf16 v[160:175], v[156:159], v[176:179], v[160:175]
	ds_read_b128 v[156:159], v207 offset:8192
	ds_read_b128 v[188:191], v207 offset:8704
	v_mfma_f32_32x32x16_bf16 v[128:143], v[128:131], v[132:135], 0
	v_mfma_f32_32x32x16_bf16 v[160:175], v[148:151], v[144:147], v[160:175]
	s_waitcnt lgkmcnt(0)
	v_mfma_f32_32x32x16_bf16 v[128:143], v[156:159], v[176:179], v[128:143]
	v_mfma_f32_32x32x16_bf16 v[160:175], v[184:187], v[180:183], v[160:175]
	v_mfma_f32_32x32x16_bf16 v[128:143], v[152:155], v[144:147], v[128:143]
	s_nop 10
	v_max3_f32 v206, v160, v161, v162
	v_max3_f32 v206, v206, v163, v164
	v_max3_f32 v206, v206, v165, v166
	v_max3_f32 v206, v206, v167, v168
	v_mfma_f32_32x32x16_bf16 v[128:143], v[188:191], v[180:183], v[128:143]
	v_max3_f32 v206, v206, v169, v170
	v_max3_f32 v206, v206, v171, v172
	v_max3_f32 v206, v206, v173, v174
	v_max_f32_e32 v206, v206, v175
	s_nop 8
	v_max3_f32 v206, v206, v128, v129
	v_max3_f32 v206, v206, v130, v131
	v_max3_f32 v206, v206, v132, v133
	v_max3_f32 v206, v206, v134, v135
	v_max3_f32 v206, v206, v136, v137
	v_max3_f32 v206, v206, v138, v139
	v_max3_f32 v206, v206, v140, v141
	v_max3_f32 v206, v206, v142, v143
	v_cmp_lt_f32_e64 vcc, v217, |v206|
	s_mov_b64 s[6:7], -1
	s_nop 1
	s_cmp_eq_u64 vcc, 0
	s_cbranch_scc0 .Lda_trans0
; DI unsigned pk2(float lo, float hi) { bf2_t v = __builtin_convertvector((f32x2){lo, hi}, bf2_t); return __builtin_bit_cast(unsigned, v); }
; #define MFMA32(a, b, c) __builtin_amdgcn_mfma_f32_32x32x16_bf16((a), (b), (c), 0, 0, 0)
; #define WAIT_V(n) asm volatile("s_waitcnt vmcnt(" #n ")" ::: "memory")
; #define BAR __builtin_amdgcn_s_barrier()
; #define WAIT_V(n) asm volatile("s_waitcnt vmcnt(" #n ")" ::: "memory")
; #define BAR do { __builtin_amdgcn_sched_barrier(0); __builtin_amdgcn_s_barrier(); asm volatile("" ::: "memory"); __builtin_amdgcn_sched_barrier(0); } while (0)
; DI void dattn_unit2(const bf16_t* __restrict__ Qg, const bf16_t* __restrict__ Kg, const bf16_t* __restrict__ Vg, bf16_t* __restrict__ Og,
;                     int ntiles, int wave_tiles, float lam, const float* __restrict__ gsub, lds_t* shm) {
;     ...
;       float rs = 0.f;
; #pragma unroll
;       for (int kb = 0; kb < 2; ++kb)
; #pragma unroll
;         for (int s2 = 0; s2 < 2; ++s2) {
;           float e[8];
; #pragma unroll
;           for (int j = 0; j < 8; ++j) { e[j] = __builtin_amdgcn_exp2f(s[kb][8 * s2 + j] - msub); rs += e[j]; }
;           u32x4 w; w.x = pk2(e[0], e[1]); w.y = pk2(e[2], e[3]); w.z = pk2(e[4], e[5]); w.w = pk2(e[6], e[7]);
;           P[m][kb][s2] = __builtin_bit_cast(bf16x8, w);
;           __builtin_amdgcn_sched_barrier(0);
;         }
;       lrun[m] += rs;
;       __builtin_amdgcn_sched_barrier(0);
;     }
;     __builtin_amdgcn_sched_barrier(0);
;     WAIT_V(4); BAR;
;     issueV(kt + 2, slot2);
;     lds_t* V0 = shm + (so + va0); lds_t* V1 = shm + (so + va1);
; #pragma unroll
;     for (int m = 0; m < 2; ++m)
;       if (resc[m]) {
; #pragma unroll
;         for (int c = 0; c < NC; ++c) O[m][c] = O[m][c] * alpha[m];
;       }
; #pragma unroll
;     for (int ks = 0; ks < 4; ++ks) {
;       bf16x8 vf[NC];
; #pragma unroll
;       for (int c = 0; c < NC; ++c) { const int vo = 512 * c + 4096 * ks; vf[c] = tr_pair(V0 + vo, V1 + vo + 2048); }
; #pragma unroll
;       for (int c = 0; c < NC; ++c) { O[0][c] = MFMA32(vf[c], P[0][ks >> 1][ks & 1], O[0][c]); O[1][c] = MFMA32(vf[c], P[1][ks >> 1][ks & 1], O[1][c]); }
;     }
	ds_read_b128 v[144:147], v202 offset:1024
	ds_read_b128 v[148:151], v225 offset:1024
	ds_read_b128 v[208:211], v225 offset:1536
	ds_read_b128 v[226:229], v202 offset:1536
	v_exp_f32_e32 v160, v160
	v_exp_f32_e32 v161, v161
	v_exp_f32_e32 v162, v162
	v_exp_f32_e32 v163, v163
	v_add_f32_e32 v201, v201, v160
	v_exp_f32_e32 v164, v164
	v_add_f32_e32 v201, v201, v161
	v_cvt_pk_bf16_f32 v160, v160, v161
	v_exp_f32_e32 v165, v165
	v_add_f32_e32 v201, v201, v162
	s_waitcnt lgkmcnt(0)
	v_mfma_f32_32x32x16_bf16 v[176:191], v[144:147], v[148:151], 0
	ds_read_b128 v[144:147], v202 offset:9216
	ds_read_b128 v[230:233], v202 offset:9728
	ds_read_b128 v[234:237], v207 offset:1024
	ds_read_b128 v[238:241], v242 offset:1024
	ds_read_b128 v[242:245], v242 offset:1536
	ds_read_b128 v[246:249], v207 offset:1536
	v_exp_f32_e32 v166, v166
	v_add_f32_e32 v201, v201, v163
	v_cvt_pk_bf16_f32 v161, v162, v163
	v_exp_f32_e32 v167, v167
	v_add_f32_e32 v201, v201, v164
	v_exp_f32_e32 v168, v168
	v_add_f32_e32 v201, v201, v165
	v_cvt_pk_bf16_f32 v162, v164, v165
	v_exp_f32_e32 v169, v169
	v_add_f32_e32 v201, v201, v166
	v_exp_f32_e32 v170, v170
	v_add_f32_e32 v201, v201, v167
	s_waitcnt lgkmcnt(0)
	v_mfma_f32_32x32x16_bf16 v[176:191], v[234:237], v[238:241], v[176:191]
	ds_read_b128 v[234:237], v207 offset:9216
	ds_read_b128 v[250:253], v207 offset:9728
	v_cvt_pk_bf16_f32 v163, v166, v167
	v_exp_f32_e32 v171, v171
	v_add_f32_e32 v201, v201, v168
	v_mfma_f32_32x32x16_bf16 v[144:159], v[144:147], v[148:151], 0
	v_exp_f32_e32 v172, v172
	v_add_f32_e32 v201, v201, v169
	v_cvt_pk_bf16_f32 v164, v168, v169
	v_exp_f32_e32 v173, v173
	v_add_f32_e32 v201, v201, v170
	v_mfma_f32_32x32x16_bf16 v[176:191], v[226:229], v[208:211], v[176:191]
	v_exp_f32_e32 v174, v174
	v_add_f32_e32 v201, v201, v171
	v_cvt_pk_bf16_f32 v165, v170, v171
	v_exp_f32_e32 v175, v175
	v_add_f32_e32 v201, v201, v172
	s_waitcnt lgkmcnt(0)
	v_mfma_f32_32x32x16_bf16 v[144:159], v[234:237], v[238:241], v[144:159]
	v_add_f32_e32 v201, v201, v173
	v_cvt_pk_bf16_f32 v166, v172, v173
	v_add_f32_e32 v201, v201, v174
	v_add_f32_e32 v201, v201, v175
	v_cvt_pk_bf16_f32 v167, v174, v175
	v_mfma_f32_32x32x16_bf16 v[176:191], v[246:249], v[242:245], v[176:191]
	v_mfma_f32_32x32x16_bf16 v[144:159], v[230:233], v[208:211], v[144:159]
	v_mfma_f32_32x32x16_bf16 v[144:159], v[250:253], v[242:245], v[144:159]
	s_nop 9
	v_max3_f32 v207, v176, v177, v178
	v_max3_f32 v207, v207, v179, v180
	v_max3_f32 v207, v207, v181, v182
	v_max3_f32 v207, v207, v183, v184
	v_max3_f32 v207, v207, v185, v186
	v_max3_f32 v207, v207, v187, v188
	v_max3_f32 v207, v207, v189, v190
	v_max_f32_e32 v207, v207, v191
	v_max3_f32 v207, v207, v144, v145
	v_max3_f32 v207, v207, v146, v147
	v_max3_f32 v207, v207, v148, v149
	v_max3_f32 v207, v207, v150, v151
	v_max3_f32 v207, v207, v152, v153
	v_max3_f32 v207, v207, v154, v155
	v_max3_f32 v207, v207, v156, v157
	v_max3_f32 v207, v207, v158, v159
	v_cmp_lt_f32_e64 s[4:5], v217, |v207|
	s_nop 1
	s_cmp_eq_u64 s[4:5], 0
	s_mov_b64 s[4:5], -1
	s_cbranch_scc0 .Lda_trans1
.Ldaf_w1:
	s_waitcnt vmcnt(4)
	s_barrier
	s_setprio 1
	s_add_i32 m0, s62, 0xc000
	s_add_u32 s64, s28, s63
	s_addc_u32 s65, s29, 0
	global_load_lds_dwordx4 v192, s[64:65]
	s_add_i32 m0, s62, 0xe000
	s_cmp_gt_i32 s60, s54
	global_load_lds_dwordx4 v196, s[64:65]
	s_cbranch_scc1 .Ldaf_w2
	v_add_u32_e32 v204, s61, v255
	v_add_u32_e32 v205, s61, v195
	ds_read_b64_tr_b16 v[226:227], v204 offset:49152
	ds_read_b64_tr_b16 v[228:229], v205 offset:51200
	ds_read_b64_tr_b16 v[230:231], v204 offset:49664
	ds_read_b64_tr_b16 v[232:233], v205 offset:51712
	ds_read_b64_tr_b16 v[234:235], v204 offset:50176
	ds_read_b64_tr_b16 v[236:237], v205 offset:52224
	ds_read_b64_tr_b16 v[238:239], v204 offset:50688
	ds_read_b64_tr_b16 v[240:241], v205 offset:52736
	v_exp_f32_e32 v176, v176
	v_exp_f32_e32 v177, v177
	v_exp_f32_e32 v178, v178
	v_exp_f32_e32 v179, v179
	v_add_f32_e32 v200, v200, v176
	v_exp_f32_e32 v180, v180
	v_add_f32_e32 v200, v200, v177
	v_cvt_pk_bf16_f32 v176, v176, v177
	v_exp_f32_e32 v181, v181
	v_add_f32_e32 v200, v200, v178
	v_exp_f32_e32 v182, v182
	v_add_f32_e32 v200, v200, v179
	v_cvt_pk_bf16_f32 v177, v178, v179
	v_exp_f32_e32 v183, v183
	v_add_f32_e32 v200, v200, v180
	v_add_f32_e32 v200, v200, v181
	v_cvt_pk_bf16_f32 v178, v180, v181
	v_add_f32_e32 v200, v200, v182
	v_add_f32_e32 v200, v200, v183
	v_cvt_pk_bf16_f32 v179, v182, v183
	s_waitcnt lgkmcnt(0)
	ds_read_b64_tr_b16 v[242:243], v204 offset:53248
	ds_read_b64_tr_b16 v[244:245], v205 offset:55296
	ds_read_b64_tr_b16 v[246:247], v204 offset:53760
	ds_read_b64_tr_b16 v[248:249], v205 offset:55808
	ds_read_b64_tr_b16 v[250:251], v204 offset:54272
	ds_read_b64_tr_b16 v[252:253], v205 offset:56320
	ds_read_b64_tr_b16 v[208:209], v204 offset:54784
	ds_read_b64_tr_b16 v[210:211], v205 offset:56832
	v_mfma_f32_32x32x16_bf16 v[96:111], v[226:229], v[160:163], v[96:111]
	v_exp_f32_e32 v184, v184
	v_exp_f32_e32 v185, v185
	v_exp_f32_e32 v186, v186
	v_exp_f32_e32 v187, v187
	v_mfma_f32_32x32x16_bf16 v[64:79], v[230:233], v[160:163], v[64:79]
	v_add_f32_e32 v200, v200, v184
	v_exp_f32_e32 v188, v188
	v_add_f32_e32 v200, v200, v185
	v_cvt_pk_bf16_f32 v180, v184, v185
	v_mfma_f32_32x32x16_bf16 v[32:47], v[234:237], v[160:163], v[32:47]
	v_exp_f32_e32 v189, v189
	v_add_f32_e32 v200, v200, v186
	v_exp_f32_e32 v190, v190
	v_add_f32_e32 v200, v200, v187
	v_mfma_f32_32x32x16_bf16 v[0:15], v[238:241], v[160:163], v[0:15]
	v_cvt_pk_bf16_f32 v181, v186, v187
	v_exp_f32_e32 v191, v191
	v_add_f32_e32 v200, v200, v188
	v_add_f32_e32 v200, v200, v189
	v_mfma_f32_32x32x16_bf16 v[112:127], v[226:229], v[176:179], v[112:127]
	v_cvt_pk_bf16_f32 v182, v188, v189
	v_add_f32_e32 v200, v200, v190
	v_add_f32_e32 v200, v200, v191
	v_cvt_pk_bf16_f32 v183, v190, v191
	v_mfma_f32_32x32x16_bf16 v[80:95], v[230:233], v[176:179], v[80:95]
	v_exp_f32_e32 v128, v128
	v_exp_f32_e32 v129, v129
	v_exp_f32_e32 v130, v130
	v_exp_f32_e32 v131, v131
	v_mfma_f32_32x32x16_bf16 v[48:63], v[234:237], v[176:179], v[48:63]
	v_add_f32_e32 v201, v201, v128
	v_exp_f32_e32 v132, v132
	v_add_f32_e32 v201, v201, v129
	v_cvt_pk_bf16_f32 v168, v128, v129
	v_mfma_f32_32x32x16_bf16 v[16:31], v[238:241], v[176:179], v[16:31]
	v_exp_f32_e32 v133, v133
	v_add_f32_e32 v201, v201, v130
	v_exp_f32_e32 v134, v134
	v_add_f32_e32 v201, v201, v131
	s_waitcnt lgkmcnt(0)
; DI bf16_t* slot(const Params& p, int i) { return (bf16_t*)(p.ws + OFF_SLOT + (size_t)i * SLOT); }
; #define MFMA32(a, b, c) __builtin_amdgcn_mfma_f32_32x32x16_bf16((a), (b), (c), 0, 0, 0)
; #define WAIT_V(n) asm volatile("s_waitcnt vmcnt(" #n ")" ::: "memory")
; #define BAR __builtin_amdgcn_s_barrier()
; #define WAIT_V(n) asm volatile("s_waitcnt vmcnt(" #n ")" ::: "memory")
; #define BAR do { __builtin_amdgcn_sched_barrier(0); __builtin_amdgcn_s_barrier(); asm volatile("" ::: "memory"); __builtin_amdgcn_sched_barrier(0); } while (0)
; DI void dattn_unit2(const bf16_t* __restrict__ Qg, const bf16_t* __restrict__ Kg, const bf16_t* __restrict__ Vg, bf16_t* __restrict__ Og,
;                     int ntiles, int wave_tiles, float lam, const float* __restrict__ gsub, lds_t* shm) {
;     ...
;     for (int ks = 0; ks < 4; ++ks) {
;       bf16x8 vf[NC];
; #pragma unroll
;       for (int c = 0; c < NC; ++c) { const int vo = 512 * c + 4096 * ks; vf[c] = tr_pair(V0 + vo, V1 + vo + 2048); }
; #pragma unroll
;       for (int c = 0; c < NC; ++c) { O[0][c] = MFMA32(vf[c], P[0][ks >> 1][ks & 1], O[0][c]); O[1][c] = MFMA32(vf[c], P[1][ks >> 1][ks & 1], O[1][c]); }
;     }
;     __builtin_amdgcn_sched_barrier(0);
;     WAIT_V(4); BAR;
;     slot = slot == 2 ? 0 : slot + 1;
;   }
	ds_read_b64_tr_b16 v[226:227], v204 offset:57344
	ds_read_b64_tr_b16 v[228:229], v205 offset:59392
	ds_read_b64_tr_b16 v[230:231], v204 offset:57856
	ds_read_b64_tr_b16 v[232:233], v205 offset:59904
	ds_read_b64_tr_b16 v[234:235], v204 offset:58368
	ds_read_b64_tr_b16 v[236:237], v205 offset:60416
	ds_read_b64_tr_b16 v[238:239], v204 offset:58880
	ds_read_b64_tr_b16 v[240:241], v205 offset:60928
	v_mfma_f32_32x32x16_bf16 v[96:111], v[242:245], v[164:167], v[96:111]
	v_cvt_pk_bf16_f32 v169, v130, v131
	v_exp_f32_e32 v135, v135
	v_add_f32_e32 v201, v201, v132
	v_add_f32_e32 v201, v201, v133
	v_mfma_f32_32x32x16_bf16 v[64:79], v[246:249], v[164:167], v[64:79]
	v_cvt_pk_bf16_f32 v170, v132, v133
	v_add_f32_e32 v201, v201, v134
	v_add_f32_e32 v201, v201, v135
	v_cvt_pk_bf16_f32 v171, v134, v135
	v_mfma_f32_32x32x16_bf16 v[32:47], v[250:253], v[164:167], v[32:47]
	v_exp_f32_e32 v144, v144
	v_exp_f32_e32 v145, v145
	v_exp_f32_e32 v146, v146
	v_exp_f32_e32 v147, v147
	v_mfma_f32_32x32x16_bf16 v[0:15], v[208:211], v[164:167], v[0:15]
	v_add_f32_e32 v200, v200, v144
	v_exp_f32_e32 v148, v148
	v_add_f32_e32 v200, v200, v145
	v_cvt_pk_bf16_f32 v184, v144, v145
	v_mfma_f32_32x32x16_bf16 v[112:127], v[242:245], v[180:183], v[112:127]
	v_exp_f32_e32 v149, v149
	v_add_f32_e32 v200, v200, v146
	v_exp_f32_e32 v150, v150
	v_add_f32_e32 v200, v200, v147
	v_mfma_f32_32x32x16_bf16 v[80:95], v[246:249], v[180:183], v[80:95]
	v_cvt_pk_bf16_f32 v185, v146, v147
	v_exp_f32_e32 v151, v151
	v_add_f32_e32 v200, v200, v148
	v_add_f32_e32 v200, v200, v149
	v_mfma_f32_32x32x16_bf16 v[48:63], v[250:253], v[180:183], v[48:63]
	v_cvt_pk_bf16_f32 v186, v148, v149
	v_add_f32_e32 v200, v200, v150
	v_add_f32_e32 v200, v200, v151
	v_cvt_pk_bf16_f32 v187, v150, v151
	v_mfma_f32_32x32x16_bf16 v[16:31], v[208:211], v[180:183], v[16:31]
	v_exp_f32_e32 v136, v136
	v_exp_f32_e32 v137, v137
	v_exp_f32_e32 v138, v138
	v_exp_f32_e32 v139, v139
	s_waitcnt lgkmcnt(0)
	ds_read_b64_tr_b16 v[242:243], v204 offset:61440
	ds_read_b64_tr_b16 v[244:245], v205 offset:63488
	ds_read_b64_tr_b16 v[246:247], v204 offset:61952
	ds_read_b64_tr_b16 v[248:249], v205 offset:64000
	ds_read_b64_tr_b16 v[250:251], v204 offset:62464
	ds_read_b64_tr_b16 v[252:253], v205 offset:64512
	ds_read_b64_tr_b16 v[208:209], v204 offset:62976
	ds_read_b64_tr_b16 v[210:211], v205 offset:65024
	v_mfma_f32_32x32x16_bf16 v[96:111], v[226:229], v[168:171], v[96:111]
	v_add_f32_e32 v201, v201, v136
	v_exp_f32_e32 v140, v140
	v_add_f32_e32 v201, v201, v137
	v_cvt_pk_bf16_f32 v172, v136, v137
	v_mfma_f32_32x32x16_bf16 v[64:79], v[230:233], v[168:171], v[64:79]
	v_exp_f32_e32 v141, v141
	v_add_f32_e32 v201, v201, v138
	v_exp_f32_e32 v142, v142
	v_add_f32_e32 v201, v201, v139
	v_mfma_f32_32x32x16_bf16 v[32:47], v[234:237], v[168:171], v[32:47]
	v_cvt_pk_bf16_f32 v173, v138, v139
	v_exp_f32_e32 v143, v143
	v_add_f32_e32 v201, v201, v140
	v_add_f32_e32 v201, v201, v141
	v_mfma_f32_32x32x16_bf16 v[0:15], v[238:241], v[168:171], v[0:15]
	v_cvt_pk_bf16_f32 v174, v140, v141
	v_add_f32_e32 v201, v201, v142
	v_add_f32_e32 v201, v201, v143
	v_cvt_pk_bf16_f32 v175, v142, v143
	v_mfma_f32_32x32x16_bf16 v[112:127], v[226:229], v[184:187], v[112:127]
	v_exp_f32_e32 v152, v152
	v_exp_f32_e32 v153, v153
	v_exp_f32_e32 v154, v154
	v_exp_f32_e32 v155, v155
	v_mfma_f32_32x32x16_bf16 v[80:95], v[230:233], v[184:187], v[80:95]
	v_add_f32_e32 v200, v200, v152
	v_exp_f32_e32 v156, v156
	v_add_f32_e32 v200, v200, v153
	v_cvt_pk_bf16_f32 v188, v152, v153
	v_mfma_f32_32x32x16_bf16 v[48:63], v[234:237], v[184:187], v[48:63]
	v_exp_f32_e32 v157, v157
	v_add_f32_e32 v200, v200, v154
	v_exp_f32_e32 v158, v158
	v_mfma_f32_32x32x16_bf16 v[16:31], v[238:241], v[184:187], v[16:31]
	v_add_f32_e32 v200, v200, v155
	v_cvt_pk_bf16_f32 v189, v154, v155
	v_exp_f32_e32 v159, v159
	s_waitcnt lgkmcnt(0)
	v_mfma_f32_32x32x16_bf16 v[96:111], v[242:245], v[172:175], v[96:111]
	v_add_f32_e32 v200, v200, v156
	v_add_f32_e32 v200, v200, v157
	v_cvt_pk_bf16_f32 v190, v156, v157
	v_mfma_f32_32x32x16_bf16 v[64:79], v[246:249], v[172:175], v[64:79]
	v_add_f32_e32 v200, v200, v158
	v_add_f32_e32 v200, v200, v159
	v_cvt_pk_bf16_f32 v191, v158, v159
	v_mfma_f32_32x32x16_bf16 v[32:47], v[250:253], v[172:175], v[32:47]
	v_mfma_f32_32x32x16_bf16 v[0:15], v[208:211], v[172:175], v[0:15]
	v_mfma_f32_32x32x16_bf16 v[112:127], v[242:245], v[188:191], v[112:127]
	v_mfma_f32_32x32x16_bf16 v[80:95], v[246:249], v[188:191], v[80:95]
	v_mfma_f32_32x32x16_bf16 v[48:63], v[250:253], v[188:191], v[48:63]
	v_mfma_f32_32x32x16_bf16 v[16:31], v[208:211], v[188:191], v[16:31]

; DI void dattn_unit2(const bf16_t* __restrict__ Qg, const bf16_t* __restrict__ Kg, const bf16_t* __restrict__ Vg, bf16_t* __restrict__ Og,
;                     int ntiles, int wave_tiles, float lam, const float* __restrict__ gsub, lds_t* shm) {
;     ...
;   for (int kt = 0; kt < ntiles; ++kt) {
;     const int slot2 = slot >= 1 ? slot - 1 : 2;
;     issueK(kt + 2, slot2);
;     const float msk = (kt < wave_tiles) ? 0.f : -INFINITY;
;     const unsigned so = slot * 16384;
;     lds_t* K0 = shm + (so + ka0); lds_t* K2 = shm + (so + ka2);
;     bf16x8 P[2][2][2]; float alpha[2]; bool resc[2];
; #pragma unroll
;     for (int m = 0; m < 2; ++m) {
;       f32x16 s[2];
; #pragma unroll
;       for (int kb = 0; kb < 2; ++kb)
; #pragma unroll
;         for (int i = 0; i < 16; ++i) s[kb][i] = 0.f;
; #pragma unroll
;       for (int ss = 0; ss < 4; ++ss) {
;         const bf16x8 qv = *LDSP(const bf16x8, Qst + ((ss & 1) ? ka2 : ka0) + 512 * (ss >> 1) + 1024 * m);
; #pragma unroll
;         for (int kb = 0; kb < 2; ++kb) {
;           const bf16x8 kf = *LDSP(const bf16x8, ((ss & 1) ? K2 : K0) + kb * 8192 + 512 * (ss >> 1) + 1024 * m);
;           s[kb] = MFMA32(kf, qv, s[kb]);
;         }
;       }
;       float mx = s[0][0];
; #pragma unroll
;       for (int i = 1; i < 16; ++i) mx = fmaxf(mx, s[0][i]);
; #pragma unroll
;       for (int i = 0; i < 16; ++i) mx = fmaxf(mx, s[1][i]);
;       { const auto sw = __builtin_amdgcn_permlane32_swap(__float_as_uint(mx), __float_as_uint(mx), false, false); mx = fmaxf(__uint_as_float(sw[0]), __uint_as_float(sw[1])) + msk; }
;       resc[m] = __builtin_amdgcn_ballot_w64(mx > mrun[m] + 8.0f) != 0;
;       alpha[m] = 1.0f;
;       if (resc[m]) { const float mnew = fmaxf(mrun[m], mx); alpha[m] = __builtin_amdgcn_exp2f(mrun[m] - mnew); mrun[m] = mnew; lrun[m] *= alpha[m]; }
;       const float msub = mrun[m] - msk;
;       float rs = 0.f;
; #pragma unroll
;       for (int kb = 0; kb < 2; ++kb)
; #pragma unroll
;         for (int s2 = 0; s2 < 2; ++s2) {
;           float e[8];
; #pragma unroll
;           for (int j = 0; j < 8; ++j) { e[j] = __builtin_amdgcn_exp2f(s[kb][8 * s2 + j] - msub); rs += e[j]; }
;           u32x4 w; w.x = pk2(e[0], e[1]); w.y = pk2(e[2], e[3]); w.z = pk2(e[4], e[5]); w.w = pk2(e[6], e[7]);
;           P[m][kb][s2] = __builtin_bit_cast(bf16x8, w);
;           __builtin_amdgcn_sched_barrier(0);
;         }
.Ldaf_maskA:
	s_mov_b64 s[6:7], -1
	s_mov_b64 s[4:5], -1
	s_branch .Ldaf_w1
.Ldas_top:
	s_add_i32 s4, s60, 2
	s_lshl_b32 s6, s59, 14
	s_min_i32 s4, s4, s55
	s_add_i32 s5, s6, 0xffffc000
	s_cmp_gt_i32 s59, 0
	s_cselect_b32 s5, s5, 0x8000
	s_add_i32 s62, s53, s5
	s_lshl_b32 s63, s4, 17
	s_add_u32 s4, s8, s63
	s_addc_u32 s5, s9, 0
	s_mov_b32 m0, s62
	s_add_i32 s61, s6, 0
	global_load_lds_dwordx4 v192, s[4:5]
	s_add_i32 m0, s62, 0x2000
	s_cmp_gt_i32 s60, s54
	global_load_lds_dwordx4 v196, s[4:5]
	s_cbranch_scc1 .Ldas_maskA
	v_add_u32_e32 v202, s61, v218
	v_add_u32_e32 v242, s52, v219
	ds_read_b128 v[128:131], v202
	ds_read_b128 v[132:135], v225
	ds_read_b128 v[144:147], v225 offset:512
	ds_read_b128 v[148:151], v202 offset:512
	v_add_u32_e32 v207, s61, v219
	s_waitcnt lgkmcnt(0)
	v_mfma_f32_32x32x16_bf16 v[160:175], v[128:131], v[132:135], 0
	ds_read_b128 v[128:131], v202 offset:8192
	ds_read_b128 v[152:155], v202 offset:8704
	ds_read_b128 v[156:159], v207
	ds_read_b128 v[176:179], v242
	ds_read_b128 v[180:183], v242 offset:512
	ds_read_b128 v[184:187], v207 offset:512
	s_waitcnt lgkmcnt(0)
	v_mfma_f32_32x32x16_bf16 v[160:175], v[156:159], v[176:179], v[160:175]
	ds_read_b128 v[156:159], v207 offset:8192
	ds_read_b128 v[188:191], v207 offset:8704
	v_mfma_f32_32x32x16_bf16 v[128:143], v[128:131], v[132:135], 0
	v_mfma_f32_32x32x16_bf16 v[160:175], v[148:151], v[144:147], v[160:175]
	s_waitcnt lgkmcnt(0)
	v_mfma_f32_32x32x16_bf16 v[128:143], v[156:159], v[176:179], v[128:143]
	v_mfma_f32_32x32x16_bf16 v[160:175], v[184:187], v[180:183], v[160:175]
	v_mfma_f32_32x32x16_bf16 v[128:143], v[152:155], v[144:147], v[128:143]
	s_nop 10
	v_max3_f32 v206, v160, v161, v162
	v_max3_f32 v206, v206, v163, v164
	v_max3_f32 v206, v206, v165, v166
	v_max3_f32 v206, v206, v167, v168
	v_mfma_f32_32x32x16_bf16 v[128:143], v[188:191], v[180:183], v[128:143]
	v_max3_f32 v206, v206, v169, v170
	v_max3_f32 v206, v206, v171, v172
	v_max3_f32 v206, v206, v173, v174
	v_max_f32_e32 v206, v206, v175
	s_nop 8
	v_max3_f32 v206, v206, v128, v129
	v_max3_f32 v206, v206, v130, v131
	v_max3_f32 v206, v206, v132, v133
	v_max3_f32 v206, v206, v134, v135
	v_max3_f32 v206, v206, v136, v137
	v_max3_f32 v206, v206, v138, v139
	v_max3_f32 v206, v206, v140, v141
	v_max3_f32 v206, v206, v142, v143
.Ldas_cmp0:
	v_cmp_lt_f32_e32 vcc, v217, v206
	s_mov_b64 s[6:7], -1
	s_nop 1
	s_cmp_eq_u64 vcc, 0
	s_cbranch_scc1 .Ldas_nr0
	v_mov_b32_e32 v205, v206
	s_nop 1
	v_permlane32_swap_b32_e32 v206, v205
	v_max_f32_e32 v206, v206, v205
	v_max_f32_e32 v206, v199, v206
	v_sub_f32_e32 v205, v199, v206
	v_mov_b32_e32 v199, v206
	v_exp_f32_e32 v203, v205
	v_add_f32_e32 v217, 0x41000000, v206
	s_mov_b64 s[6:7], 0
	v_mul_f32_e32 v201, v201, v203
.Ldas_nr0:
	ds_read_b128 v[144:147], v202 offset:1024
	ds_read_b128 v[148:151], v225 offset:1024
	ds_read_b128 v[208:211], v225 offset:1536
	ds_read_b128 v[226:229], v202 offset:1536
	v_sub_f32_e32 v160, v160, v199
	v_sub_f32_e32 v161, v161, v199
	v_sub_f32_e32 v162, v162, v199
	v_exp_f32_e32 v160, v160
	v_sub_f32_e32 v163, v163, v199
	v_exp_f32_e32 v161, v161
	v_sub_f32_e32 v164, v164, v199
	v_exp_f32_e32 v162, v162
	v_sub_f32_e32 v165, v165, v199
	v_exp_f32_e32 v163, v163
	s_waitcnt lgkmcnt(0)
	v_mfma_f32_32x32x16_bf16 v[176:191], v[144:147], v[148:151], 0
	ds_read_b128 v[144:147], v202 offset:9216
	ds_read_b128 v[230:233], v202 offset:9728
	ds_read_b128 v[234:237], v207 offset:1024
	ds_read_b128 v[238:241], v242 offset:1024
	ds_read_b128 v[242:245], v242 offset:1536
	ds_read_b128 v[246:249], v207 offset:1536
	v_add_f32_e32 v201, v201, v160
	v_sub_f32_e32 v166, v166, v199
	v_exp_f32_e32 v164, v164
	v_add_f32_e32 v201, v201, v161
	v_sub_f32_e32 v167, v167, v199
	v_cvt_pk_bf16_f32 v160, v160, v161
	v_exp_f32_e32 v165, v165
	v_add_f32_e32 v201, v201, v162
	v_sub_f32_e32 v168, v168, v199
	v_exp_f32_e32 v166, v166
	v_add_f32_e32 v201, v201, v163
	v_sub_f32_e32 v169, v169, v199
	s_waitcnt lgkmcnt(0)
	v_mfma_f32_32x32x16_bf16 v[176:191], v[234:237], v[238:241], v[176:191]
	ds_read_b128 v[234:237], v207 offset:9216
	ds_read_b128 v[250:253], v207 offset:9728
	v_cvt_pk_bf16_f32 v161, v162, v163
	v_exp_f32_e32 v167, v167
	v_add_f32_e32 v201, v201, v164
	v_mfma_f32_32x32x16_bf16 v[144:159], v[144:147], v[148:151], 0
	v_sub_f32_e32 v170, v170, v199
	v_exp_f32_e32 v168, v168
	v_add_f32_e32 v201, v201, v165
	v_sub_f32_e32 v171, v171, v199
	v_cvt_pk_bf16_f32 v162, v164, v165
	v_mfma_f32_32x32x16_bf16 v[176:191], v[226:229], v[208:211], v[176:191]
	v_exp_f32_e32 v169, v169
	v_add_f32_e32 v201, v201, v166
	v_sub_f32_e32 v172, v172, v199
	v_exp_f32_e32 v170, v170
	v_add_f32_e32 v201, v201, v167
	s_waitcnt lgkmcnt(0)
	v_mfma_f32_32x32x16_bf16 v[144:159], v[234:237], v[238:241], v[144:159]
	v_sub_f32_e32 v173, v173, v199
	v_cvt_pk_bf16_f32 v163, v166, v167
	v_exp_f32_e32 v171, v171
	v_add_f32_e32 v201, v201, v168
	v_sub_f32_e32 v174, v174, v199
	v_mfma_f32_32x32x16_bf16 v[176:191], v[246:249], v[242:245], v[176:191]
	v_exp_f32_e32 v172, v172
	v_add_f32_e32 v201, v201, v169
	v_sub_f32_e32 v175, v175, v199
	v_cvt_pk_bf16_f32 v164, v168, v169
	v_exp_f32_e32 v173, v173
	v_mfma_f32_32x32x16_bf16 v[144:159], v[230:233], v[208:211], v[144:159]
	v_add_f32_e32 v201, v201, v170
	v_exp_f32_e32 v174, v174
	v_add_f32_e32 v201, v201, v171
	v_cvt_pk_bf16_f32 v165, v170, v171
	v_exp_f32_e32 v175, v175
	v_mfma_f32_32x32x16_bf16 v[144:159], v[250:253], v[242:245], v[144:159]
	v_max3_f32 v207, v176, v177, v178
	v_add_f32_e32 v201, v201, v172
	v_add_f32_e32 v201, v201, v173
	v_max3_f32 v207, v207, v179, v180
	v_cvt_pk_bf16_f32 v166, v172, v173
	v_add_f32_e32 v201, v201, v174
	v_max3_f32 v207, v207, v181, v182
	v_add_f32_e32 v201, v201, v175
	v_cvt_pk_bf16_f32 v167, v174, v175
	v_max3_f32 v207, v207, v183, v184
	v_max3_f32 v207, v207, v185, v186
	v_max3_f32 v207, v207, v187, v188
	v_max3_f32 v207, v207, v189, v190
	v_max_f32_e32 v207, v207, v191
	v_max3_f32 v207, v207, v144, v145
	v_max3_f32 v207, v207, v146, v147
	v_max3_f32 v207, v207, v148, v149
	v_max3_f32 v207, v207, v150, v151
	v_max3_f32 v207, v207, v152, v153
	v_max3_f32 v207, v207, v154, v155
	v_max3_f32 v207, v207, v156, v157
	v_max3_f32 v207, v207, v158, v159
.Ldas_cmp1:
	v_cmp_lt_f32_e64 s[4:5], v197, v207
	s_nop 1
	s_cmp_eq_u64 s[4:5], 0
	s_mov_b64 s[4:5], -1
	s_cbranch_scc1 .Ldas_nr1
	v_mov_b32_e32 v205, v207
	s_nop 1
	v_permlane32_swap_b32_e32 v207, v205
	v_max_f32_e32 v207, v207, v205
	v_max_f32_e32 v207, v198, v207
	v_sub_f32_e32 v205, v198, v207
	v_mov_b32_e32 v198, v207
	v_exp_f32_e32 v202, v205
	v_add_f32_e32 v197, 0x41000000, v207
	s_mov_b64 s[4:5], 0
	v_mul_f32_e32 v200, v200, v202

; DI void dattn_unit2(const bf16_t* __restrict__ Qg, const bf16_t* __restrict__ Kg, const bf16_t* __restrict__ Vg, bf16_t* __restrict__ Og,
;                     int ntiles, int wave_tiles, float lam, const float* __restrict__ gsub, lds_t* shm) {
;     ...
;   float mrun[2] = {-INFINITY, -INFINITY}, lrun[2] = {0.f, 0.f};
;     ...
;       resc[m] = __builtin_amdgcn_ballot_w64(mx > mrun[m] + 8.0f) != 0;
;       alpha[m] = 1.0f;
;       if (resc[m]) { const float mnew = fmaxf(mrun[m], mx); alpha[m] = __builtin_amdgcn_exp2f(mrun[m] - mnew); mrun[m] = mnew; lrun[m] *= alpha[m]; }
;       const float msub = mrun[m] - msk;
.Lda_trans0:
	s_mov_b32 s98, 1
	s_cmp_eq_u32 s60, 0
	s_cbranch_scc1 .Lda_trans0_first
	v_mov_b32_e32 v199, 0
	v_mov_b32_e32 v198, 0
	v_mov_b32_e32 v217, 0x41000000
	v_mov_b32_e32 v197, 0x41000000
	s_branch .Ldas_cmp0
.Lda_trans0_first:
	v_mov_b32_e32 v199, 0xff800000
	v_mov_b32_e32 v198, 0xff800000
	v_mov_b32_e32 v217, 0xff800000
	v_mov_b32_e32 v197, 0xff800000
	s_branch .Ldas_cmp0
.Lda_trans1:
	s_mov_b32 s98, 1
	v_mov_b32_e32 v199, 0
	v_mov_b32_e32 v217, 0x41000000
	s_mov_b64 s[6:7], -1
	s_cmp_eq_u32 s60, 0
	s_cbranch_scc1 .Lda_trans1_first
	v_mov_b32_e32 v198, 0
	v_mov_b32_e32 v197, 0x41000000
	s_branch .Ldas_cmp1
.Lda_trans1_first:
	v_mov_b32_e32 v198, 0xff800000
	v_mov_b32_e32 v197, 0xff800000
	s_branch .Ldas_cmp1

; #define LDSP(T, p) ((__attribute__((address_space(3))) T*)(p))
; DI unsigned xcd_barrier_post(unsigned* bar) { const unsigned x = xb_xcc_id(); if (threadIdx.x == 0) (void)xb_add(&bar[XB_XCNT(x)], 1u); return x; }
; __global__ void __launch_bounds__(NTHR) mega_kernel(Params p) {
;   cg::grid_group grid = cg::this_grid();
;   if (p.ws == nullptr) grid.sync();
;   XcdBarrier xb; xb.bar = (unsigned*)(p.ws + OFF_BAR); xb.x = xcd_barrier_post(xb.bar);
;   { __attribute__((address_space(3))) unsigned* t = LDSP(unsigned, smem_raw);
;     if (threadIdx.x == 0) { unsigned nloc, nx; xcd_barrier_complete(xb.bar, xb.x, nloc, nx); t[0] = nloc; t[1] = nx; }
;     __syncthreads();
;     xb.nloc = __builtin_amdgcn_readfirstlane(t[0]); xb.nx = __builtin_amdgcn_readfirstlane(t[1]);
;     __syncthreads(); }
;   run_from<0>(p, (lds_t*)smem_raw, grid, xb);
; }
	.amdhsa_kernel _Z11mega_kernel6Params
		.amdhsa_group_segment_fixed_size 0
		.amdhsa_private_segment_fixed_size 0
		.amdhsa_kernarg_size 480
		.amdhsa_user_sgpr_count 2
		.amdhsa_user_sgpr_dispatch_ptr 0
		.amdhsa_user_sgpr_queue_ptr 0
		.amdhsa_user_sgpr_kernarg_segment_ptr 1
		.amdhsa_user_sgpr_dispatch_id 0
		.amdhsa_user_sgpr_kernarg_preload_length 0
		.amdhsa_user_sgpr_kernarg_preload_offset 0
		.amdhsa_user_sgpr_private_segment_size 0
		.amdhsa_uses_dynamic_stack 0
		.amdhsa_enable_private_segment 0
		.amdhsa_system_sgpr_workgroup_id_x 1
		.amdhsa_system_sgpr_workgroup_id_y 0
		.amdhsa_system_sgpr_workgroup_id_z 0
		.amdhsa_system_sgpr_workgroup_info 0
		.amdhsa_system_vgpr_workitem_id 2
		.amdhsa_next_free_vgpr 256
		.amdhsa_next_free_sgpr 102
		.amdhsa_accum_offset 256
		.amdhsa_reserve_vcc 1
		.amdhsa_float_round_mode_32 0
		.amdhsa_float_round_mode_16_64 0
		.amdhsa_float_denorm_mode_32 3
		.amdhsa_float_denorm_mode_16_64 3
		.amdhsa_dx10_clamp 1
		.amdhsa_ieee_mode 1
		.amdhsa_fp16_overflow 0
		.amdhsa_tg_split 0
		.amdhsa_exception_fp_ieee_invalid_op 0
		.amdhsa_exception_fp_denorm_src 0
		.amdhsa_exception_fp_ieee_div_zero 0
		.amdhsa_exception_fp_ieee_overflow 0
		.amdhsa_exception_fp_ieee_underflow 0
		.amdhsa_exception_fp_ieee_inexact 0
		.amdhsa_exception_int_div_zero 0
	.end_amdhsa_kernel

; #define LDSP(T, p) ((__attribute__((address_space(3))) T*)(p))
; DI unsigned xcd_barrier_post(unsigned* bar) { const unsigned x = xb_xcc_id(); if (threadIdx.x == 0) (void)xb_add(&bar[XB_XCNT(x)], 1u); return x; }
; __global__ void __launch_bounds__(NTHR) mega_kernel(Params p) {
;   cg::grid_group grid = cg::this_grid();
;   if (p.ws == nullptr) grid.sync();
;   XcdBarrier xb; xb.bar = (unsigned*)(p.ws + OFF_BAR); xb.x = xcd_barrier_post(xb.bar);
;   { __attribute__((address_space(3))) unsigned* t = LDSP(unsigned, smem_raw);
;     if (threadIdx.x == 0) { unsigned nloc, nx; xcd_barrier_complete(xb.bar, xb.x, nloc, nx); t[0] = nloc; t[1] = nx; }
;     __syncthreads();
;     xb.nloc = __builtin_amdgcn_readfirstlane(t[0]); xb.nx = __builtin_amdgcn_readfirstlane(t[1]);
;     __syncthreads(); }
;   run_from<0>(p, (lds_t*)smem_raw, grid, xb);
; }
amdhsa.kernels:
  - .agpr_count:     0
    .args:
      - .offset:         0
        .size:           224
        .value_kind:     by_value
      - .offset:         224
        .size:           4
        .value_kind:     hidden_block_count_x
      - .offset:         228
        .size:           4
        .value_kind:     hidden_block_count_y
      - .offset:         232
        .size:           4
        .value_kind:     hidden_block_count_z
      - .offset:         236
        .size:           2
        .value_kind:     hidden_group_size_x
      - .offset:         238
        .size:           2
        .value_kind:     hidden_group_size_y
      - .offset:         240
        .size:           2
        .value_kind:     hidden_group_size_z
      - .offset:         242
        .size:           2
        .value_kind:     hidden_remainder_x
      - .offset:         244
        .size:           2
        .value_kind:     hidden_remainder_y
      - .offset:         246
        .size:           2
        .value_kind:     hidden_remainder_z
      - .offset:         264
        .size:           8
        .value_kind:     hidden_global_offset_x
      - .offset:         272
        .size:           8
        .value_kind:     hidden_global_offset_y
      - .offset:         280
        .size:           8
        .value_kind:     hidden_global_offset_z
      - .offset:         288
        .size:           2
        .value_kind:     hidden_grid_dims
      - .offset:         312
        .size:           8
        .value_kind:     hidden_multigrid_sync_arg
      - .offset:         344
        .size:           4
        .value_kind:     hidden_dynamic_lds_size
    .group_segment_fixed_size: 0
    .kernarg_segment_align: 8
    .kernarg_segment_size: 480
    .language:       OpenCL C
    .language_version:
      - 2
      - 0
    .max_flat_workgroup_size: 512
    .name:           _Z11mega_kernel6Params
    .private_segment_fixed_size: 0
    .sgpr_count:     108
    .sgpr_spill_count: 132
    .symbol:         _Z11mega_kernel6Params.kd
    .uniform_work_group_size: 1
    .uses_dynamic_stack: false
    .vgpr_count:     256
    .vgpr_spill_count: 0
    .wavefront_size: 64
